# v6 + waves 4-7 lagged by s_sleep 6 at attention tile start (de-phase the two waves per SIMD)
# speedup vs baseline: 1.0030x; 1.0021x over previous
; #define LAS __attribute__((address_space(3)))
; #define A_LOAD(t) do { kreg0 = *(const u32x4*)(kg + (size_t)((t) * 64 + kv0) * 768 + kc0 * 8); if (tid < 256) kreg1 = *(const u32x4*)(kg + (size_t)((t) * 64 + kv1) * 768 + kc1 * 8); \
;         vreg = *(const u32x4*)(vg + (size_t)(t) * 64 * 512); } while (0)
; __device__ __forceinline__ void attn_unit(LAS unsigned char* lds, const bf16* Q, const bf16* Kp, const bf16* V, bf16* Y, int b, int h, int qb) {
;     ...
;     for (int t = 0; t < NT; ++t) {
;         const int buf = t & 1;
;         if (t + 1 < NT) A_LOAD(t + 1);
;         const int jb = t - (NT - 4);
;         const bool skip = (jb >= 0) && (64 * jb > wid * 32 + 31);
;         if (!skip) {
;             f32x16 p0, p1;
;             const float nm = -m_run;
; #pragma unroll
;             for (int i = 0; i < 16; ++i) { p0[i] = nm; p1[i] = nm; }
;             LAS const unsigned char* kb = lds + KOFF + buf * KBUF + r32 * KPB + hi * 16;
;             LAS const unsigned char* vb = lds + VOFF + buf * VBUF + r32 * VPB + hi * 8;
; #pragma unroll
;             for (int d0 = 0; d0 < 6; ++d0) p0 = __builtin_amdgcn_mfma_f32_32x32x16_bf16(*(LAS const bf16x8*)(kb + 32 * d0), qr[d0], p0, 0, 0, 0);
; #pragma unroll
;             for (int d0 = 0; d0 < 6; ++d0) p1 = __builtin_amdgcn_mfma_f32_32x32x16_bf16(*(LAS const bf16x8*)(kb + 32 * KPB + 32 * d0), qr[d0], p1, 0, 0, 0);
.Lat_noload:
	s_add_i32 s10, s13, -1
	s_and_b32 s24, s10, 1
	s_add_i32 s10, s22, s13
	s_addk_i32 s10, 0xff83
	s_cmp_gt_i32 s10, -1
	s_cselect_b64 s[10:11], -1, 0
	s_add_i32 s25, s15, s23
	s_addk_i32 s25, 0xe100
	s_cmp_gt_i32 s25, s14
	s_cselect_b64 s[26:27], -1, 0
	s_and_b64 s[26:27], s[10:11], s[26:27]
	s_and_b64 vcc, exec, s[26:27]
	s_cbranch_vccnz .Lat_stage
	s_and_b64 vcc, exec, s[38:39]
	s_cbranch_vccnz .Lat_nolag
	s_sleep 6
.Lat_nolag:
	s_mul_i32 s25, s24, 0x3400
	v_add_u32_e32 v110, s25, v117
	s_mul_i32 s25, s24, 0x2200
	v_add_u32_e32 v125, s25, v118
	ds_read_b128 v[172:175], v110
	ds_read_b128 v[176:179], v110 offset:32
	ds_read_b128 v[180:183], v110 offset:64
	ds_read_b128 v[184:187], v110 offset:96
	ds_read_b128 v[188:191], v110 offset:128
	ds_read_b128 v[192:195], v110 offset:160
	ds_read_b128 v[198:201], v110 offset:6656
	ds_read_b128 v[202:205], v110 offset:6688
	ds_read_b128 v[206:209], v110 offset:6720
	ds_read_b128 v[222:225], v110 offset:6752
	ds_read_b128 v[226:229], v110 offset:6784
	ds_read_b128 v[230:233], v110 offset:6816
	v_add_u32_e32 v124, 0x6800, v125
	v_add_u32_e32 v125, 0x7800, v125
	s_waitcnt lgkmcnt(11)
	v_mfma_f32_32x32x16_bf16 v[32:47], v[172:175], v[68:71], v[142:157]
	ds_read2_b64 v[234:237], v124 offset1:2
	s_waitcnt lgkmcnt(11)
	v_mfma_f32_32x32x16_bf16 v[32:47], v[176:179], v[72:75], v[32:47]
	ds_read2_b64 v[238:241], v124 offset0:4 offset1:6
	s_waitcnt lgkmcnt(11)
	v_mfma_f32_32x32x16_bf16 v[32:47], v[180:183], v[76:79], v[32:47]
	ds_read2_b64 v[242:245], v125 offset0:32 offset1:34
	s_waitcnt lgkmcnt(11)
	v_mfma_f32_32x32x16_bf16 v[32:47], v[184:187], v[80:83], v[32:47]
	ds_read2_b64 v[246:249], v125 offset0:36 offset1:38
	s_waitcnt lgkmcnt(11)
	v_mfma_f32_32x32x16_bf16 v[32:47], v[188:191], v[84:87], v[32:47]
	s_waitcnt lgkmcnt(10)
	v_mfma_f32_32x32x16_bf16 v[32:47], v[192:195], v[88:91], v[32:47]
	s_waitcnt lgkmcnt(9)
	v_mfma_f32_32x32x16_bf16 v[48:63], v[198:201], v[68:71], v[142:157]
	s_waitcnt lgkmcnt(8)
	v_mfma_f32_32x32x16_bf16 v[48:63], v[202:205], v[72:75], v[48:63]
	s_waitcnt lgkmcnt(7)
	v_mfma_f32_32x32x16_bf16 v[48:63], v[206:209], v[76:79], v[48:63]
	s_nop 5
	s_andn2_b64 vcc, exec, s[10:11]
	s_cbranch_vccnz .Lat_nomask0
	v_add_u32_e32 v126, s23, v119
	v_sub_u32_e32 v126, v116, v126
	v_add_u32_e32 v126, 0x1f00, v126
	v_cmp_gt_i32_e32 vcc, 0, v126
	v_cmp_gt_i32_e64 s[40:41], 1, v126
	v_cmp_gt_i32_e64 s[42:43], 2, v126
	v_cndmask_b32_e32 v32, v32, v221, vcc
	v_cmp_gt_i32_e32 vcc, 3, v126
	v_cndmask_b32_e64 v33, v33, v221, s[40:41]
	v_cmp_gt_i32_e64 s[40:41], 8, v126
	v_cndmask_b32_e64 v34, v34, v221, s[42:43]
	v_cmp_gt_i32_e64 s[42:43], 9, v126
	v_cndmask_b32_e32 v35, v35, v221, vcc
	v_cmp_gt_i32_e32 vcc, 10, v126
	v_cndmask_b32_e64 v36, v36, v221, s[40:41]
	v_cmp_gt_i32_e64 s[40:41], 11, v126
	v_cndmask_b32_e64 v37, v37, v221, s[42:43]
	v_cmp_gt_i32_e64 s[42:43], 16, v126
	v_cndmask_b32_e32 v38, v38, v221, vcc
	v_cmp_gt_i32_e32 vcc, 17, v126
	v_cndmask_b32_e64 v39, v39, v221, s[40:41]
	v_cmp_gt_i32_e64 s[40:41], 18, v126
	v_cndmask_b32_e64 v40, v40, v221, s[42:43]
	v_cmp_gt_i32_e64 s[42:43], 19, v126
	v_cndmask_b32_e32 v41, v41, v221, vcc
	v_cmp_gt_i32_e32 vcc, 24, v126
	v_cndmask_b32_e64 v42, v42, v221, s[40:41]
	v_cmp_gt_i32_e64 s[40:41], 25, v126
	v_cndmask_b32_e64 v43, v43, v221, s[42:43]
	v_cmp_gt_i32_e64 s[42:43], 26, v126
	v_cndmask_b32_e32 v44, v44, v221, vcc
	v_cmp_gt_i32_e32 vcc, 27, v126
	v_cndmask_b32_e64 v45, v45, v221, s[40:41]
	v_cndmask_b32_e64 v46, v46, v221, s[42:43]
	s_nop 0
	v_cndmask_b32_e32 v47, v47, v221, vcc
